# P11 last column tile (pn=48, 224 of 256 weight rows are the prologue's zero padding): 16-MFMA clusters whose weight half-tile is all padding are skipped (wave-uniform branch; acc stays +0 exactly)
# speedup vs baseline: 1.0022x; 1.0022x over previous
; __device__ __forceinline__ int lane_id() { int l; asm volatile("v_mbcnt_lo_u32_b32 %0, -1, 0\n\tv_mbcnt_hi_u32_b32 %0, -1, %0" : "=v"(l)); return l; }
; template <class Epi, class Sched, bool ALIGN_EPI>
; __device__ __forceinline__ void gemm_phase(LAS unsigned char* lds, const Gemm g, const Sched& S, const Epi& E, const int wid) {
;     const int lane = lane_id(), tid = wid * 64 + lane, wr = wid >> 2, wc = wid & 3, fr = lane & 15, fq = lane >> 4;
;     const int K = g.K, nt = K / BK;
; __global__ void __launch_bounds__(NTHR, 2) mega_fwd(Args) {
;     ...
;         pg8::Gemm g{WSP(bf16_t, WS_XB), WSP(bf16_t, WS_W_IN1), 64, 64, DM, 32768, (size_t)BM_ * DM * 2, 32768, (size_t)BM_ * DM * 2}; pg8::StaticOrder S; S.init(MTOK, FOX_INP, G, bx);
.LBB0_919:
	s_mov_b32 s32, 0
	s_cmp_lg_u32 s18, 48
	s_cbranch_scc1 .Lp11flag_done
	v_readlane_b32 s32, v248, 4
	s_nop 3
	s_and_b32 s32, s32, 3
	s_cmp_lg_u32 s32, 0
	s_cselect_b32 s32, 3, 2

; #define PG8_STAGE(bufoff, gbase, voff) do { _Pragma("unroll") for (int _i = 0; _i < 2; ++_i) \
;         __builtin_amdgcn_global_load_lds((const unsigned*)((const char*)(gbase) + (voff)[_i]), (LAS unsigned*)(lds + (bufoff) + ldsw + _i * 8192), 16, 0, 0); } while (0)
; #define PG8_LDA(dst, b, h) do { _Pragma("unroll") for (int m = 0; m < 4; ++m) _Pragma("unroll") for (int k = 0; k < 2; ++k) dst[m][k] = *(const LAS bf16x8*)(lds + PG8_SA(b, h) + aoff + m * 2048 + k * 1024); } while (0)
; #define PG8_LDB(dst, b, h) do { _Pragma("unroll") for (int n = 0; n < 2; ++n) _Pragma("unroll") for (int k = 0; k < 2; ++k) dst[n][k] = *(const LAS bf16x8*)(lds + PG8_SB(b, h) + boff + n * 2048 + k * 1024); } while (0)
; #define PG8_MMA(ai, bj, At, Bt) do { __builtin_amdgcn_s_setprio(1); _Pragma("unroll") for (int m = 0; m < 4; ++m) _Pragma("unroll") for (int n = 0; n < 2; ++n) _Pragma("unroll") for (int k = 0; k < 2; ++k) \
;         acc[ai][bj][m][n] = __builtin_amdgcn_mfma_f32_16x16x32_bf16(Bt[n][k], At[m][k], acc[ai][bj][m][n], 0, 0, 0); __builtin_amdgcn_s_setprio(0); } while (0)
; #define PG8_WAIT_V(n) asm volatile("s_waitcnt vmcnt(" #n ")" ::: "memory")
; #define PG8_WAIT_L(n) asm volatile("s_waitcnt lgkmcnt(" #n ")" ::: "memory")
; #define PG8_BAR __builtin_amdgcn_s_barrier()
; #define PG8_SCHED __builtin_amdgcn_sched_barrier(0)
; template <class Epi, class Sched, bool ALIGN_EPI>
; __device__ __forceinline__ void gemm_phase(LAS unsigned char* lds, const Gemm g, const Sched& S, const Epi& E, const int wid) {
;     ...
;             PG8_LDB(B0, 0, 0); PG8_LDB(B1, 0, 1); PG8_SCHED; PG8_LDA(At, 0, 0); PG8_STAGE(PG8_SA(1, 1), a1 + hstepA, voffA);
;             PG8_WAIT_V(8); PG8_WAIT_L(0); PG8_BAR; PG8_MMA(0, 0, At, B0); PG8_MMA(0, 1, At, B1); PG8_BAR; PG8_SCHED;
.LBB0_920:
	v_add_u32_e32 v142, s89, v170
	s_waitcnt lgkmcnt(0)
	ds_read_b128 v[130:133], v142
	ds_read_b128 v[134:137], v142 offset:1024
	ds_read_b128 v[138:141], v142 offset:2048
	ds_read_b128 v[182:185], v142 offset:3072
	v_add_u32_e32 v142, s90, v170
	s_add_u32 s38, s68, 0x4000
	ds_read_b128 v[186:189], v142
	ds_read_b128 v[190:193], v142 offset:1024
	ds_read_b128 v[194:197], v142 offset:2048
	ds_read_b128 v[198:201], v142 offset:3072
	s_addc_u32 s39, s69, 0
	s_and_b64 s[70:71], s[72:73], exec
	s_cselect_b32 s74, s5, s38
	s_cselect_b32 s75, s4, s39
	s_add_u32 s70, s74, 0x8000
	s_addc_u32 s71, s75, 0
	s_and_b64 s[72:73], s[72:73], exec
	s_cselect_b32 s73, s19, s35
	s_cselect_b32 s72, s30, s31
	s_add_i32 m0, s44, 0xc000
	ds_read_b128 v[202:205], v177
	ds_read_b128 v[206:209], v177 offset:1024
	ds_read_b128 v[210:213], v177 offset:2048
	ds_read_b128 v[214:217], v177 offset:3072
	ds_read_b128 v[218:221], v177 offset:4096
	ds_read_b128 v[222:225], v177 offset:5120
	ds_read_b128 v[226:229], v177 offset:6144
	ds_read_b128 v[230:233], v177 offset:7168
	global_load_lds_dwordx4 v158, s[68:69]
	s_add_i32 m0, s44, 0xe000
	s_nop 0
	global_load_lds_dwordx4 v160, s[68:69]
	s_waitcnt vmcnt(8)
	s_waitcnt lgkmcnt(0)
	s_barrier
	s_setprio 1
	s_waitcnt lgkmcnt(0)
	s_bitcmp1_b32 s32, 0
	s_cbranch_scc1 .Lp11skip_0
	v_mfma_f32_16x16x32_bf16 v[124:127], v[130:133], v[202:205], v[124:127]
	v_mfma_f32_16x16x32_bf16 v[120:123], v[138:141], v[202:205], v[120:123]
	v_mfma_f32_16x16x32_bf16 v[108:111], v[130:133], v[210:213], v[108:111]
	v_mfma_f32_16x16x32_bf16 v[104:107], v[138:141], v[210:213], v[104:107]
	v_mfma_f32_16x16x32_bf16 v[92:95], v[130:133], v[218:221], v[92:95]
	v_mfma_f32_16x16x32_bf16 v[88:91], v[138:141], v[218:221], v[88:91]
	v_mfma_f32_16x16x32_bf16 v[76:79], v[130:133], v[226:229], v[76:79]
	v_mfma_f32_16x16x32_bf16 v[72:75], v[138:141], v[226:229], v[72:75]
	v_mfma_f32_16x16x32_bf16 v[124:127], v[134:137], v[206:209], v[124:127]
	v_mfma_f32_16x16x32_bf16 v[120:123], v[182:185], v[206:209], v[120:123]
	v_mfma_f32_16x16x32_bf16 v[108:111], v[134:137], v[214:217], v[108:111]
	v_mfma_f32_16x16x32_bf16 v[104:107], v[182:185], v[214:217], v[104:107]
	v_mfma_f32_16x16x32_bf16 v[92:95], v[134:137], v[222:225], v[92:95]
	v_mfma_f32_16x16x32_bf16 v[88:91], v[182:185], v[222:225], v[88:91]
	v_mfma_f32_16x16x32_bf16 v[76:79], v[134:137], v[230:233], v[76:79]
	v_mfma_f32_16x16x32_bf16 v[72:75], v[182:185], v[230:233], v[72:75]
.Lp11skip_0:
	s_setprio 0
	s_setprio 1
	s_bitcmp1_b32 s32, 1
	s_cbranch_scc1 .Lp11skip_1
	v_mfma_f32_16x16x32_bf16 v[116:119], v[186:189], v[202:205], v[116:119]
	v_mfma_f32_16x16x32_bf16 v[112:115], v[194:197], v[202:205], v[112:115]
	v_mfma_f32_16x16x32_bf16 v[100:103], v[186:189], v[210:213], v[100:103]
	v_mfma_f32_16x16x32_bf16 v[96:99], v[194:197], v[210:213], v[96:99]
	v_mfma_f32_16x16x32_bf16 v[84:87], v[186:189], v[218:221], v[84:87]
	v_mfma_f32_16x16x32_bf16 v[80:83], v[194:197], v[218:221], v[80:83]
	v_mfma_f32_16x16x32_bf16 v[68:71], v[186:189], v[226:229], v[68:71]
	v_mfma_f32_16x16x32_bf16 v[64:67], v[194:197], v[226:229], v[64:67]
	v_mfma_f32_16x16x32_bf16 v[116:119], v[190:193], v[206:209], v[116:119]
	v_mfma_f32_16x16x32_bf16 v[112:115], v[198:201], v[206:209], v[112:115]
	v_mfma_f32_16x16x32_bf16 v[100:103], v[190:193], v[214:217], v[100:103]
	v_mfma_f32_16x16x32_bf16 v[96:99], v[198:201], v[214:217], v[96:99]
	v_mfma_f32_16x16x32_bf16 v[84:87], v[190:193], v[222:225], v[84:87]
	v_mfma_f32_16x16x32_bf16 v[80:83], v[198:201], v[222:225], v[80:83]
	v_mfma_f32_16x16x32_bf16 v[68:71], v[190:193], v[230:233], v[68:71]
	v_mfma_f32_16x16x32_bf16 v[64:67], v[198:201], v[230:233], v[64:67]
; #define PG8_STAGE(bufoff, gbase, voff) do { _Pragma("unroll") for (int _i = 0; _i < 2; ++_i) \
;         __builtin_amdgcn_global_load_lds((const unsigned*)((const char*)(gbase) + (voff)[_i]), (LAS unsigned*)(lds + (bufoff) + ldsw + _i * 8192), 16, 0, 0); } while (0)
; #define PG8_LDA(dst, b, h) do { _Pragma("unroll") for (int m = 0; m < 4; ++m) _Pragma("unroll") for (int k = 0; k < 2; ++k) dst[m][k] = *(const LAS bf16x8*)(lds + PG8_SA(b, h) + aoff + m * 2048 + k * 1024); } while (0)
; #define PG8_LDB(dst, b, h) do { _Pragma("unroll") for (int n = 0; n < 2; ++n) _Pragma("unroll") for (int k = 0; k < 2; ++k) dst[n][k] = *(const LAS bf16x8*)(lds + PG8_SB(b, h) + boff + n * 2048 + k * 1024); } while (0)
; #define PG8_MMA(ai, bj, At, Bt) do { __builtin_amdgcn_s_setprio(1); _Pragma("unroll") for (int m = 0; m < 4; ++m) _Pragma("unroll") for (int n = 0; n < 2; ++n) _Pragma("unroll") for (int k = 0; k < 2; ++k) \
;         acc[ai][bj][m][n] = __builtin_amdgcn_mfma_f32_16x16x32_bf16(Bt[n][k], At[m][k], acc[ai][bj][m][n], 0, 0, 0); __builtin_amdgcn_s_setprio(0); } while (0)
; #define PG8_WAIT_V(n) asm volatile("s_waitcnt vmcnt(" #n ")" ::: "memory")
; #define PG8_WAIT_L(n) asm volatile("s_waitcnt lgkmcnt(" #n ")" ::: "memory")
; #define PG8_BAR __builtin_amdgcn_s_barrier()
; #define PG8_SCHED __builtin_amdgcn_sched_barrier(0)
; template <class Epi, class Sched, bool ALIGN_EPI>
; __device__ __forceinline__ void gemm_phase(LAS unsigned char* lds, const Gemm g, const Sched& S, const Epi& E, const int wid) {
;     ...
;             PG8_LDA(At, 0, 1); PG8_STAGE(PG8_SB(0, 0), b2, voffB); PG8_STAGE(PG8_SB(0, 1), b2 + hstepB, voffB); PG8_STAGE(PG8_SA(0, 0), a2, voffA);
;             PG8_WAIT_V(8); PG8_WAIT_L(0); PG8_BAR; PG8_MMA(1, 0, At, B0); PG8_MMA(1, 1, At, B1); PG8_BAR; PG8_SCHED;
;             PG8_LDB(B0, 1, 0); PG8_LDB(B1, 1, 1); PG8_SCHED; PG8_LDA(At, 1, 0); PG8_STAGE(PG8_SA(0, 1), a2 + hstepA, voffA);
;             PG8_WAIT_V(8); PG8_WAIT_L(0); PG8_BAR; PG8_MMA(0, 0, At, B0); PG8_MMA(0, 1, At, B1); PG8_BAR; PG8_SCHED;
.Lp11skip_1:
	s_setprio 0
	s_barrier
	s_add_i32 s38, s89, s3
	s_mov_b32 m0, s38
	ds_read_b128 v[202:205], v177 offset:16384
	ds_read_b128 v[206:209], v177 offset:17408
	ds_read_b128 v[210:213], v177 offset:18432
	ds_read_b128 v[214:217], v177 offset:19456
	ds_read_b128 v[218:221], v177 offset:20480
	ds_read_b128 v[222:225], v177 offset:21504
	ds_read_b128 v[226:229], v177 offset:22528
	ds_read_b128 v[230:233], v177 offset:23552
	global_load_lds_dwordx4 v146, s[72:73]
	s_add_i32 m0, s38, 0x2000
	s_add_u32 s94, s72, 0x1000
	s_addc_u32 s95, s73, 0
	s_add_i32 s38, s90, s3
	global_load_lds_dwordx4 v150, s[72:73]
	s_mov_b32 m0, s38
	s_nop 0
	global_load_lds_dwordx4 v146, s[94:95]
	s_add_i32 m0, s38, 0x2000
	s_nop 0
	global_load_lds_dwordx4 v150, s[94:95]
	s_mov_b32 m0, s44
	s_nop 0
	global_load_lds_dwordx4 v144, s[74:75]
	s_mov_b32 m0, s45
	s_nop 0
	global_load_lds_dwordx4 v148, s[74:75]
	s_waitcnt vmcnt(8)
	s_waitcnt lgkmcnt(0)
	s_barrier
	s_setprio 1
	s_waitcnt lgkmcnt(0)
	s_bitcmp1_b32 s32, 0
	s_cbranch_scc1 .Lp11skip_2
	v_mfma_f32_16x16x32_bf16 v[60:63], v[130:133], v[202:205], v[60:63]
	v_mfma_f32_16x16x32_bf16 v[56:59], v[138:141], v[202:205], v[56:59]
	v_mfma_f32_16x16x32_bf16 v[44:47], v[130:133], v[210:213], v[44:47]
	v_mfma_f32_16x16x32_bf16 v[40:43], v[138:141], v[210:213], v[40:43]
	v_mfma_f32_16x16x32_bf16 v[28:31], v[130:133], v[218:221], v[28:31]
	v_mfma_f32_16x16x32_bf16 v[24:27], v[138:141], v[218:221], v[24:27]
	v_mfma_f32_16x16x32_bf16 v[12:15], v[130:133], v[226:229], v[12:15]
	v_mfma_f32_16x16x32_bf16 v[8:11], v[138:141], v[226:229], v[8:11]
	v_mfma_f32_16x16x32_bf16 v[60:63], v[134:137], v[206:209], v[60:63]
	v_mfma_f32_16x16x32_bf16 v[56:59], v[182:185], v[206:209], v[56:59]
	v_mfma_f32_16x16x32_bf16 v[44:47], v[134:137], v[214:217], v[44:47]
	v_mfma_f32_16x16x32_bf16 v[40:43], v[182:185], v[214:217], v[40:43]
	v_mfma_f32_16x16x32_bf16 v[28:31], v[134:137], v[222:225], v[28:31]
	v_mfma_f32_16x16x32_bf16 v[24:27], v[182:185], v[222:225], v[24:27]
	v_mfma_f32_16x16x32_bf16 v[12:15], v[134:137], v[230:233], v[12:15]
	v_mfma_f32_16x16x32_bf16 v[8:11], v[182:185], v[230:233], v[8:11]
.Lp11skip_2:
	s_setprio 0
	s_setprio 1
	s_bitcmp1_b32 s32, 1
	s_cbranch_scc1 .Lp11skip_3
	v_mfma_f32_16x16x32_bf16 v[52:55], v[186:189], v[202:205], v[52:55]
	v_mfma_f32_16x16x32_bf16 v[48:51], v[194:197], v[202:205], v[48:51]
	v_mfma_f32_16x16x32_bf16 v[36:39], v[186:189], v[210:213], v[36:39]
	v_mfma_f32_16x16x32_bf16 v[32:35], v[194:197], v[210:213], v[32:35]
	v_mfma_f32_16x16x32_bf16 v[20:23], v[186:189], v[218:221], v[20:23]
	v_mfma_f32_16x16x32_bf16 v[16:19], v[194:197], v[218:221], v[16:19]
	v_mfma_f32_16x16x32_bf16 v[4:7], v[186:189], v[226:229], v[4:7]
	v_mfma_f32_16x16x32_bf16 v[0:3], v[194:197], v[226:229], v[0:3]
	v_mfma_f32_16x16x32_bf16 v[52:55], v[190:193], v[206:209], v[52:55]
	v_mfma_f32_16x16x32_bf16 v[48:51], v[198:201], v[206:209], v[48:51]
	v_mfma_f32_16x16x32_bf16 v[36:39], v[190:193], v[214:217], v[36:39]
	v_mfma_f32_16x16x32_bf16 v[32:35], v[198:201], v[214:217], v[32:35]
	v_mfma_f32_16x16x32_bf16 v[20:23], v[190:193], v[222:225], v[20:23]
	v_mfma_f32_16x16x32_bf16 v[16:19], v[198:201], v[222:225], v[16:19]
	v_mfma_f32_16x16x32_bf16 v[4:7], v[190:193], v[230:233], v[4:7]
	v_mfma_f32_16x16x32_bf16 v[0:3], v[198:201], v[230:233], v[0:3]
.Lp11skip_3:
	s_setprio 0
	s_barrier
	s_add_i32 s38, 0, 0x18000
	v_add_u32_e32 v142, s38, v170
	s_add_i32 s39, 0, 0x1c000
	ds_read_b128 v[130:133], v142
	ds_read_b128 v[134:137], v142 offset:1024
	ds_read_b128 v[138:141], v142 offset:2048
	ds_read_b128 v[182:185], v142 offset:3072
	v_add_u32_e32 v142, s39, v170
	ds_read_b128 v[186:189], v142
	ds_read_b128 v[190:193], v142 offset:1024
	ds_read_b128 v[194:197], v142 offset:2048
	ds_read_b128 v[198:201], v142 offset:3072
	s_add_u32 s74, s74, 0x4000
	s_addc_u32 s75, s75, 0
	s_mov_b32 m0, s46
	ds_read_b128 v[202:205], v177 offset:32768
	ds_read_b128 v[206:209], v177 offset:33792
	ds_read_b128 v[210:213], v177 offset:34816
	ds_read_b128 v[214:217], v177 offset:35840
	ds_read_b128 v[218:221], v177 offset:36864
	ds_read_b128 v[222:225], v177 offset:37888
	ds_read_b128 v[226:229], v177 offset:38912
	ds_read_b128 v[230:233], v177 offset:39936
	global_load_lds_dwordx4 v144, s[74:75]
	s_mov_b32 m0, s47
	s_nop 0
	global_load_lds_dwordx4 v148, s[74:75]
	s_waitcnt vmcnt(8)
	s_waitcnt lgkmcnt(0)
	s_barrier
	s_setprio 1
	s_waitcnt lgkmcnt(0)
	s_bitcmp1_b32 s32, 0
	s_cbranch_scc1 .Lp11skip_4
	v_mfma_f32_16x16x32_bf16 v[124:127], v[130:133], v[202:205], v[124:127]
	v_mfma_f32_16x16x32_bf16 v[120:123], v[138:141], v[202:205], v[120:123]
	v_mfma_f32_16x16x32_bf16 v[108:111], v[130:133], v[210:213], v[108:111]
	v_mfma_f32_16x16x32_bf16 v[104:107], v[138:141], v[210:213], v[104:107]
	v_mfma_f32_16x16x32_bf16 v[92:95], v[130:133], v[218:221], v[92:95]
	v_mfma_f32_16x16x32_bf16 v[88:91], v[138:141], v[218:221], v[88:91]
	v_mfma_f32_16x16x32_bf16 v[76:79], v[130:133], v[226:229], v[76:79]
	v_mfma_f32_16x16x32_bf16 v[72:75], v[138:141], v[226:229], v[72:75]
	v_mfma_f32_16x16x32_bf16 v[124:127], v[134:137], v[206:209], v[124:127]
	v_mfma_f32_16x16x32_bf16 v[120:123], v[182:185], v[206:209], v[120:123]
	v_mfma_f32_16x16x32_bf16 v[108:111], v[134:137], v[214:217], v[108:111]
	v_mfma_f32_16x16x32_bf16 v[104:107], v[182:185], v[214:217], v[104:107]
	v_mfma_f32_16x16x32_bf16 v[92:95], v[134:137], v[222:225], v[92:95]
	v_mfma_f32_16x16x32_bf16 v[88:91], v[182:185], v[222:225], v[88:91]
	v_mfma_f32_16x16x32_bf16 v[76:79], v[134:137], v[230:233], v[76:79]
	v_mfma_f32_16x16x32_bf16 v[72:75], v[182:185], v[230:233], v[72:75]

; #define PG8_STAGE(bufoff, gbase, voff) do { _Pragma("unroll") for (int _i = 0; _i < 2; ++_i) \
;         __builtin_amdgcn_global_load_lds((const unsigned*)((const char*)(gbase) + (voff)[_i]), (LAS unsigned*)(lds + (bufoff) + ldsw + _i * 8192), 16, 0, 0); } while (0)
; #define PG8_LDA(dst, b, h) do { _Pragma("unroll") for (int m = 0; m < 4; ++m) _Pragma("unroll") for (int k = 0; k < 2; ++k) dst[m][k] = *(const LAS bf16x8*)(lds + PG8_SA(b, h) + aoff + m * 2048 + k * 1024); } while (0)
; #define PG8_MMA(ai, bj, At, Bt) do { __builtin_amdgcn_s_setprio(1); _Pragma("unroll") for (int m = 0; m < 4; ++m) _Pragma("unroll") for (int n = 0; n < 2; ++n) _Pragma("unroll") for (int k = 0; k < 2; ++k) \
;         acc[ai][bj][m][n] = __builtin_amdgcn_mfma_f32_16x16x32_bf16(Bt[n][k], At[m][k], acc[ai][bj][m][n], 0, 0, 0); __builtin_amdgcn_s_setprio(0); } while (0)
; #define PG8_WAIT_V(n) asm volatile("s_waitcnt vmcnt(" #n ")" ::: "memory")
; #define PG8_WAIT_L(n) asm volatile("s_waitcnt lgkmcnt(" #n ")" ::: "memory")
; #define PG8_BAR __builtin_amdgcn_s_barrier()
; #define PG8_SCHED __builtin_amdgcn_sched_barrier(0)
; template <class Epi, class Sched, bool ALIGN_EPI>
; __device__ __forceinline__ void gemm_phase(LAS unsigned char* lds, const Gemm g, const Sched& S, const Epi& E, const int wid) {
;     ...
;             PG8_LDA(At, 1, 1); PG8_STAGE(PG8_SB(1, 0), b3, voffB); PG8_STAGE(PG8_SB(1, 1), b3 + hstepB, voffB); PG8_STAGE(PG8_SA(1, 0), a3, voffA);
;             PG8_WAIT_V(8); PG8_WAIT_L(0); PG8_BAR; PG8_MMA(1, 0, At, B0); PG8_MMA(1, 1, At, B1); PG8_BAR; PG8_SCHED;
.Lp11skip_5:
	s_setprio 0
	s_barrier
	s_add_u32 s74, s72, 0x8000
	s_addc_u32 s75, s73, 0
	s_add_i32 s38, s38, s3
	s_mov_b32 m0, s38
	ds_read_b128 v[202:205], v177 offset:49152
	ds_read_b128 v[206:209], v177 offset:50176
	ds_read_b128 v[210:213], v177 offset:51200
	ds_read_b128 v[214:217], v177 offset:52224
	ds_read_b128 v[218:221], v177 offset:53248
	ds_read_b128 v[222:225], v177 offset:54272
	ds_read_b128 v[226:229], v177 offset:55296
	ds_read_b128 v[230:233], v177 offset:56320
	global_load_lds_dwordx4 v146, s[74:75]
	s_add_i32 m0, s38, 0x2000
	s_add_u32 s72, s72, 0x9000
	s_addc_u32 s73, s73, 0
	s_add_i32 s38, s39, s3
	global_load_lds_dwordx4 v150, s[74:75]
	s_mov_b32 m0, s38
	s_nop 0
	global_load_lds_dwordx4 v146, s[72:73]
	s_add_i32 m0, s38, 0x2000
	s_nop 0
	global_load_lds_dwordx4 v150, s[72:73]
	s_mov_b32 m0, s79
	s_nop 0
	global_load_lds_dwordx4 v144, s[70:71]
	s_mov_b32 m0, s80
	s_nop 0
	global_load_lds_dwordx4 v148, s[70:71]
	s_waitcnt vmcnt(8)
	s_waitcnt lgkmcnt(0)
	s_barrier
	s_setprio 1
	s_waitcnt lgkmcnt(0)
	s_bitcmp1_b32 s32, 0
	s_cbranch_scc1 .Lp11skip_6
	v_mfma_f32_16x16x32_bf16 v[60:63], v[130:133], v[202:205], v[60:63]
	v_mfma_f32_16x16x32_bf16 v[56:59], v[138:141], v[202:205], v[56:59]
	v_mfma_f32_16x16x32_bf16 v[44:47], v[130:133], v[210:213], v[44:47]
	v_mfma_f32_16x16x32_bf16 v[40:43], v[138:141], v[210:213], v[40:43]
	v_mfma_f32_16x16x32_bf16 v[28:31], v[130:133], v[218:221], v[28:31]
	v_mfma_f32_16x16x32_bf16 v[24:27], v[138:141], v[218:221], v[24:27]
	v_mfma_f32_16x16x32_bf16 v[12:15], v[130:133], v[226:229], v[12:15]
	v_mfma_f32_16x16x32_bf16 v[8:11], v[138:141], v[226:229], v[8:11]
	v_mfma_f32_16x16x32_bf16 v[60:63], v[134:137], v[206:209], v[60:63]
	v_mfma_f32_16x16x32_bf16 v[56:59], v[182:185], v[206:209], v[56:59]
	v_mfma_f32_16x16x32_bf16 v[44:47], v[134:137], v[214:217], v[44:47]
	v_mfma_f32_16x16x32_bf16 v[40:43], v[182:185], v[214:217], v[40:43]
	v_mfma_f32_16x16x32_bf16 v[28:31], v[134:137], v[222:225], v[28:31]
	v_mfma_f32_16x16x32_bf16 v[24:27], v[182:185], v[222:225], v[24:27]
	v_mfma_f32_16x16x32_bf16 v[12:15], v[134:137], v[230:233], v[12:15]
	v_mfma_f32_16x16x32_bf16 v[8:11], v[182:185], v[230:233], v[8:11]

; #define PG8_MMA(ai, bj, At, Bt) do { __builtin_amdgcn_s_setprio(1); _Pragma("unroll") for (int m = 0; m < 4; ++m) _Pragma("unroll") for (int n = 0; n < 2; ++n) _Pragma("unroll") for (int k = 0; k < 2; ++k) \
;         acc[ai][bj][m][n] = __builtin_amdgcn_mfma_f32_16x16x32_bf16(Bt[n][k], At[m][k], acc[ai][bj][m][n], 0, 0, 0); __builtin_amdgcn_s_setprio(0); } while (0)
; #define PG8_WAIT_V(n) asm volatile("s_waitcnt vmcnt(" #n ")" ::: "memory")
; #define PG8_WAIT_L(n) asm volatile("s_waitcnt lgkmcnt(" #n ")" ::: "memory")
; #define PG8_BAR __builtin_amdgcn_s_barrier()
; #define PG8_SCHED __builtin_amdgcn_sched_barrier(0)
; template <class Epi, class Sched, bool ALIGN_EPI>
; __device__ __forceinline__ void gemm_phase(LAS unsigned char* lds, const Gemm g, const Sched& S, const Epi& E, const int wid) {
;     ...
;         for (int t = 0; t < nt; t += 2) {
;     ...
;             PG8_WAIT_V(8); PG8_WAIT_L(0); PG8_BAR; PG8_MMA(1, 0, At, B0); PG8_MMA(1, 1, At, B1); PG8_BAR; PG8_SCHED;
.Lp11skip_7:
	s_setprio 0
	s_barrier
	s_add_i32 s54, s54, 2
	s_add_u32 s68, s68, 0x10000
	s_addc_u32 s69, s69, 0
	s_add_u32 s31, s31, 0x10000
	s_addc_u32 s35, s35, 0
	s_cmp_gt_u32 s54, 61
	s_cbranch_scc1 .LBB0_923
